# v29: v28 + attention/GLA/norm/combine loop heads aligned to 64 bytes
# baseline (speedup 1.0000x reference)
; __device__ __forceinline__ float wave_sum(float v) {
; #pragma unroll
;     for (int o = 32; o >= 1; o >>= 1) v += __shfl_xor(v, o);
;     return v;
; __device__ __forceinline__ void phase_norm(const Frame& F, const float* xl, const float* xc, const f16* x16, int l, int which, int r0, int nrows, int ci, int nc) {
;     const float* nw = F.in[6] + ((size_t)l * 3 + which) * DM;
;     const int gw = r0 + ci * 8 + F.wave, nw_ = nc * 8;
;     for (int row = gw; row < nrows; row += nw_) {
;         const bool lat = row < TL; const int mi = lat ? (row >> 12) : 8;
;         const float* sh = F.MOD + ((size_t)l * 9 + mi) * NMOD + (3 * which) * DM; const float* sc = sh + DM;
;         float v[2][8]; float ss = 0.f;
;         if (x16) {
;             const f16* xp = x16 + (size_t)row * DM;
; #pragma unroll
;             for (int j = 0; j < 2; ++j) { const f16x8 t = *(const f16x8*)(xp + j * 512 + F.lane * 8);
.LBB0_405:
	s_or_b64 exec, exec, s[4:5]
	s_lshl_b32 s2, s56, 3
	s_add_i32 s4, s2, s0
	s_cmpk_gt_i32 s4, 0x7fff
	s_barrier
	s_cbranch_scc1 .LBB0_408
	v_and_b32_e32 v0, 64, v237
	v_add_u32_e32 v0, 64, v0
	v_xor_b32_e32 v2, 32, v237
	v_cmp_lt_i32_e32 vcc, v2, v0
	s_lshl_b32 s6, s1, 3
	v_readlane_b32 s0, v254, 27
	v_cndmask_b32_e32 v2, v237, v2, vcc
	v_lshlrev_b32_e32 v8, 2, v2
	v_xor_b32_e32 v2, 16, v237
	v_cmp_lt_i32_e32 vcc, v2, v0
	s_add_u32 s0, s20, s0
	v_readlane_b32 s1, v254, 26
	v_cndmask_b32_e32 v2, v237, v2, vcc
	v_lshlrev_b32_e32 v9, 2, v2
	v_xor_b32_e32 v2, 8, v237
	v_cmp_lt_i32_e32 vcc, v2, v0
	s_addc_u32 s1, s21, s1
	s_add_u32 s0, s0, 0x1000
	v_cndmask_b32_e32 v2, v237, v2, vcc
	v_lshlrev_b32_e32 v10, 2, v2
	v_xor_b32_e32 v2, 4, v237
	v_cmp_lt_i32_e32 vcc, v2, v0
	v_lshlrev_b32_e32 v16, 3, v14
	s_addc_u32 s1, s1, 0
	v_cndmask_b32_e32 v2, v237, v2, vcc
	v_lshlrev_b32_e32 v11, 2, v2
	v_xor_b32_e32 v2, 2, v237
	v_cmp_lt_i32_e32 vcc, v2, v0
	v_or_b32_e32 v18, 0x200, v16
	s_ashr_i32 s5, s4, 31
	v_cndmask_b32_e32 v2, v237, v2, vcc
	v_lshlrev_b32_e32 v12, 2, v2
	v_xor_b32_e32 v2, 1, v237
	v_cmp_lt_i32_e32 vcc, v2, v0
	s_mov_b32 s3, 0xfbc00000
	v_readlane_b32 s12, v254, 28
	v_cndmask_b32_e32 v0, v237, v2, vcc
	v_lshlrev_b32_e32 v13, 2, v0
	v_lshlrev_b32_e32 v0, 5, v14
	v_lshl_add_u64 v[2:3], s[0:1], 0, v[0:1]
	v_lshlrev_b32_e32 v0, 2, v18
	v_lshl_add_u64 v[4:5], s[0:1], 0, v[0:1]
	s_lshl_b64 s[0:1], s[4:5], 11
	s_add_u32 s0, s18, s0
	v_lshlrev_b32_e32 v0, 4, v14
	s_addc_u32 s1, s19, s1
	v_lshl_add_u64 v[6:7], s[0:1], 0, v[0:1]
	s_mov_b64 s[0:1], 0x6948000
	s_ashr_i32 s7, s6, 31
	v_lshl_add_u64 v[6:7], v[6:7], 0, s[0:1]
	s_lshl_b64 s[8:9], s[6:7], 11
	v_lshlrev_b32_e32 v0, 2, v16
	v_lshlrev_b32_e32 v14, 2, v18
	s_mov_b32 s5, 0xfbc01000
	v_readlane_b32 s7, v254, 29
	.p2align	6

; __device__ __forceinline__ void phase_qkprep(const Frame& F, int l, bool last, int ci, int nc) {
;     ...
;     for (int row = gw; row < TT; row += nw_) {
;         const bool lat = row < TL;
;         float cs[16], sn[16];
;         if (lat) { const int t = row & 4095, pos = (j < 4) ? (t >> 6) : (t & 63); const float* tp = F.ROPE + (pos * 32 + (j & 1) * 16) * 2;
; #pragma unroll
;             for (int q4 = 0; q4 < 8; ++q4) { const f32x4 v = *(const f32x4*)(tp + q4 * 4); cs[q4 * 2] = v[0]; sn[q4 * 2] = v[1]; cs[q4 * 2 + 1] = v[2]; sn[q4 * 2 + 1] = v[3]; } }
;         else {
; #pragma unroll
;             for (int e = 0; e < 16; ++e) { cs[e] = 1.f; sn[e] = 0.f; } }
;         f16* zp = F.Z + (size_t)row * ZLD;
; #pragma unroll
;         for (int pass = 0; pass < 2; ++pass) {
;             if (pass == 0 && !lat && last) continue;
;             if (pass == 1 && hd >= 2) continue;
.LBB0_580:
	s_or_b64 exec, exec, s[26:27]
	s_add_i32 s0, s0, s2
	s_cmp_lt_i32 s0, 0x8800
	v_lshl_add_u64 v[66:67], v[66:67], 0, s[10:11]
	s_cbranch_scc0 .LBB0_587
	.p2align	6

; __device__ __forceinline__ void phase_attn(const Frame& F, int l, bool last, int ai, int na) {
;     ...
;         const float sk = sinkp[hq] * 1.4426950408889634f;
;         float mrun = sk, lrun = 1.0f;
;         f32x16 oacc[4];
; #pragma unroll
;         for (int dt = 0; dt < 4; ++dt)
; #pragma unroll
;             for (int e = 0; e < 16; ++e) oacc[dt][e] = 0.f;
;         int wlo = 0, nwin = 0;
;         if (!isctx) { const int lo = (qb == 0) ? 0 : qb * 128 - 128, hi = (qb == 31) ? SEQ : qb * 128 + 256; wlo = lo; nwin = (hi - lo) >> 6; }
;         const int ntile = nwin + 4;
;         const int qpos = qb * 128 + (w & 3) * 32 + r32;
;         u32x4 k0, k1, v0, v1;
;     ...
;         AT_LOAD(0);
;     ...
;         __syncthreads();
;         AT_STORE(0);
;         if (ntile > 1) AT_LOAD(1);
;         for (int t = 0; t < ntile; ++t) {
;             const int bo = (t & 1) * AT_BUF;
;             __syncthreads();
;             if (t + 1 < ntile) { AT_STORE(AT_BUF - bo); if (t + 2 < ntile) AT_LOAD(t + 2); }
;             const int kpos0 = wlo + t * 64, q0w = qb * 128 + (w & 3) * 32;
;             const bool win = (t < nwin) && !(kpos0 <= q0w + 65 && kpos0 >= q0w - 97);
;             if ((t < nwin) && (kpos0 > q0w + 159 || kpos0 < q0w - 191)) continue;
.LBB0_608:
	v_mul_f32_e32 v230, 0x3fb8aa3b, v2
	v_add_u32_e32 v0, s27, v164
	v_add_u32_e32 v2, s2, v225
	v_mov_b32_e32 v14, v1
	v_mov_b32_e32 v15, v1
	s_or_b32 s37, s2, s14
	s_lshl_b32 s10, s3, 1
	s_mov_b32 s11, s92
	v_sub_u32_e32 v229, v0, v2
	v_mov_b32_e32 v0, v1
	v_mov_b32_e32 v2, v1
	v_mov_b32_e32 v3, v1
	v_mov_b32_e32 v4, v1
	v_mov_b32_e32 v5, v1
	v_mov_b32_e32 v6, v1
	v_mov_b32_e32 v7, v1
	v_mov_b32_e32 v8, v1
	v_mov_b32_e32 v9, v1
	v_mov_b32_e32 v10, v1
	v_mov_b32_e32 v11, v1
	v_mov_b32_e32 v12, v1
	v_mov_b32_e32 v13, v1
	v_mov_b64_e32 v[78:79], v[14:15]
	v_mov_b64_e32 v[62:63], v[14:15]
	v_mov_b64_e32 v[46:47], v[14:15]
	v_mov_b64_e32 v[30:31], v[14:15]
	s_add_i32 s31, s28, 4
	s_add_i32 s34, s37, 0x41
	s_add_i32 s35, s37, 0xffffff9f
	s_add_i32 s36, s37, 0x9f
	s_addk_i32 s37, 0xff41
	v_lshl_add_u64 v[174:175], v[166:167], 0, s[10:11]
	v_lshl_add_u64 v[176:177], v[168:169], 0, s[10:11]
	v_mov_b32_e32 v171, 1.0
	s_mov_b32 s38, 0
	s_mov_b32 s39, -4
	v_mov_b64_e32 v[76:77], v[12:13]
	v_mov_b64_e32 v[74:75], v[10:11]
	v_mov_b64_e32 v[72:73], v[8:9]
	v_mov_b64_e32 v[70:71], v[6:7]
	v_mov_b64_e32 v[68:69], v[4:5]
	v_mov_b64_e32 v[66:67], v[2:3]
	v_mov_b64_e32 v[64:65], v[0:1]
	v_mov_b64_e32 v[60:61], v[12:13]
	v_mov_b64_e32 v[58:59], v[10:11]
	v_mov_b64_e32 v[56:57], v[8:9]
	v_mov_b64_e32 v[54:55], v[6:7]
	v_mov_b64_e32 v[52:53], v[4:5]
	v_mov_b64_e32 v[50:51], v[2:3]
	v_mov_b64_e32 v[48:49], v[0:1]
	v_mov_b64_e32 v[44:45], v[12:13]
	v_mov_b64_e32 v[42:43], v[10:11]
	v_mov_b64_e32 v[40:41], v[8:9]
	v_mov_b64_e32 v[38:39], v[6:7]
	v_mov_b64_e32 v[36:37], v[4:5]
	v_mov_b64_e32 v[34:35], v[2:3]
	v_mov_b64_e32 v[32:33], v[0:1]
	v_mov_b64_e32 v[28:29], v[12:13]
	v_mov_b64_e32 v[26:27], v[10:11]
	v_mov_b64_e32 v[24:25], v[8:9]
	v_mov_b64_e32 v[22:23], v[6:7]
	v_mov_b64_e32 v[20:21], v[4:5]
	v_mov_b64_e32 v[18:19], v[2:3]
	v_mov_b64_e32 v[16:17], v[0:1]
	.p2align	6

; __device__ __forceinline__ void phase_attn(const Frame& F, int l, bool last, int ai, int na) {
;     ...
;             if (anyupd) { const float alpha = __builtin_amdgcn_exp2f(mrun - mnew); lrun *= alpha;
; #pragma unroll
;                 for (int dt = 0; dt < 4; ++dt)
; #pragma unroll
;                     for (int e = 0; e < 16; ++e) oacc[dt][e] *= alpha; }
;             lrun += rs; mrun = mnew;
.LBB0_619:
	v_mov_b32_e32 v230, v0
	s_branch .LBB0_609
	.p2align	6

; #define LAS __attribute__((address_space(3)))
; __device__ __forceinline__ void phase_attn(const Frame& F, int l, bool last, int ai, int na) {
;     ...
;             float rs = 0.f;
; #pragma unroll
;             for (int kt = 0; kt < 2; ++kt)
; #pragma unroll
;                 for (int g4 = 0; g4 < 4; ++g4) { float pv4[4];
; #pragma unroll
;                     for (int e = 0; e < 4; ++e) { pv4[e] = __builtin_amdgcn_exp2f(sacc[kt][g4 * 4 + e] - mnew); rs += pv4[e]; }
;                     *(LAS u32x2*)(Pw + (r32 * 72 + kt * 32 + g4 * 8 + hh * 4) * 2) = (u32x2){pk_f16(pv4[0], pv4[1]), pk_f16(pv4[2], pv4[3])}; }
;             rs += __shfl_xor(rs, 32);
;             if (anyupd) { const float alpha = __builtin_amdgcn_exp2f(mrun - mnew); lrun *= alpha;
; #pragma unroll
;                 for (int dt = 0; dt < 4; ++dt)
; #pragma unroll
;                     for (int e = 0; e < 16; ++e) oacc[dt][e] *= alpha; }
;             lrun += rs; mrun = mnew;
;             asm volatile("s_waitcnt lgkmcnt(0)" ::: "memory");
; #pragma unroll
;             for (int s = 0; s < 4; ++s) { const f16x8 pb = *(const LAS f16x8*)(Pw + (r32 * 72 + s * 16 + hh * 8) * 2);
; #pragma unroll
;                 for (int dt = 0; dt < 4; ++dt) { const f16x8 a = *(const LAS f16x8*)(lds + bo + AT_V + ((dt * 32 + r32) * 72 + s * 16 + hh * 8) * 2);
;                     oacc[dt] = __builtin_amdgcn_mfma_f32_32x32x16_f16(a, pb, oacc[dt], 0, 0, 0); } }
.Lnm_norescale:
	v_sub_f32_e32 v6, v96, v0
	v_exp_f32_e32 v6, v6
	v_sub_f32_e32 v7, v97, v0
	v_exp_f32_e32 v7, v7
	v_sub_f32_e32 v8, v98, v0
	v_exp_f32_e32 v8, v8
	v_sub_f32_e32 v9, v99, v0
	v_exp_f32_e32 v9, v9
	v_add_f32_e32 v14, v14, v6
	v_add_f32_e32 v14, v14, v7
	v_add_f32_e32 v14, v14, v8
	v_add_f32_e32 v14, v14, v9
	v_cvt_pk_f16_f32 v2, v6, v7
	v_cvt_pk_f16_f32 v3, v8, v9
	v_sub_f32_e32 v6, v100, v0
	v_exp_f32_e32 v6, v6
	v_sub_f32_e32 v7, v101, v0
	v_exp_f32_e32 v7, v7
	v_sub_f32_e32 v8, v102, v0
	v_exp_f32_e32 v8, v8
	v_sub_f32_e32 v9, v103, v0
	v_exp_f32_e32 v9, v9
	v_add_f32_e32 v14, v14, v6
	v_add_f32_e32 v14, v14, v7
	v_add_f32_e32 v14, v14, v8
	v_add_f32_e32 v14, v14, v9
	v_cvt_pk_f16_f32 v4, v6, v7
	v_cvt_pk_f16_f32 v5, v8, v9
	ds_write2_b64 v228, v[2:3], v[4:5] offset1:2
	v_sub_f32_e32 v6, v104, v0
	v_exp_f32_e32 v6, v6
	v_sub_f32_e32 v7, v105, v0
	v_exp_f32_e32 v7, v7
	v_sub_f32_e32 v8, v106, v0
	v_exp_f32_e32 v8, v8
	v_sub_f32_e32 v9, v107, v0
	v_exp_f32_e32 v9, v9
	v_add_f32_e32 v14, v14, v6
	v_add_f32_e32 v14, v14, v7
	v_add_f32_e32 v14, v14, v8
	v_add_f32_e32 v14, v14, v9
	v_cvt_pk_f16_f32 v2, v6, v7
	v_cvt_pk_f16_f32 v3, v8, v9
	v_sub_f32_e32 v6, v108, v0
	v_exp_f32_e32 v6, v6
	v_sub_f32_e32 v7, v109, v0
	v_exp_f32_e32 v7, v7
	v_sub_f32_e32 v8, v110, v0
	v_exp_f32_e32 v8, v8
	v_sub_f32_e32 v9, v111, v0
	v_exp_f32_e32 v9, v9
	v_add_f32_e32 v14, v14, v6
	v_add_f32_e32 v14, v14, v7
	v_add_f32_e32 v14, v14, v8
	v_add_f32_e32 v14, v14, v9
	v_cvt_pk_f16_f32 v4, v6, v7
	v_cvt_pk_f16_f32 v5, v8, v9
	ds_write2_b64 v228, v[2:3], v[4:5] offset0:4 offset1:6
	ds_read_b128 v[200:203], v12
	ds_read_b128 v[242:245], v12 offset:32
	ds_read_b128 v[96:99], v13 offset:17408
	ds_read_b128 v[100:103], v13 offset:22016
	ds_read_b128 v[104:107], v13 offset:26624
	ds_read_b128 v[108:111], v13 offset:31232
	v_sub_f32_e32 v6, v80, v0
	v_exp_f32_e32 v6, v6
	v_sub_f32_e32 v7, v81, v0
	v_exp_f32_e32 v7, v7
	v_sub_f32_e32 v8, v82, v0
	v_exp_f32_e32 v8, v8
	v_sub_f32_e32 v9, v83, v0
	s_waitcnt lgkmcnt(3)
	v_mfma_f32_32x32x16_f16 v[64:79], v[96:99], v[200:203], v[64:79]
	ds_read_b128 v[96:99], v13 offset:17440
	v_exp_f32_e32 v9, v9
	v_add_f32_e32 v14, v14, v6
	v_add_f32_e32 v14, v14, v7
	v_add_f32_e32 v14, v14, v8
	v_add_f32_e32 v14, v14, v9
	v_cvt_pk_f16_f32 v2, v6, v7
	v_cvt_pk_f16_f32 v3, v8, v9
	s_waitcnt lgkmcnt(3)
	v_mfma_f32_32x32x16_f16 v[48:63], v[100:103], v[200:203], v[48:63]
	ds_read_b128 v[100:103], v13 offset:22048
	v_sub_f32_e32 v6, v84, v0
	v_exp_f32_e32 v6, v6
	v_sub_f32_e32 v7, v85, v0
	v_exp_f32_e32 v7, v7
	v_sub_f32_e32 v8, v86, v0
	v_exp_f32_e32 v8, v8
	v_sub_f32_e32 v9, v87, v0
	s_waitcnt lgkmcnt(3)
	v_mfma_f32_32x32x16_f16 v[32:47], v[104:107], v[200:203], v[32:47]
	ds_read_b128 v[104:107], v13 offset:26656
	v_exp_f32_e32 v9, v9
	v_add_f32_e32 v14, v14, v6
	v_add_f32_e32 v14, v14, v7
	v_add_f32_e32 v14, v14, v8
	v_add_f32_e32 v14, v14, v9
	v_cvt_pk_f16_f32 v4, v6, v7
	v_cvt_pk_f16_f32 v5, v8, v9
	ds_write2_b64 v228, v[2:3], v[4:5] offset0:8 offset1:10
	s_waitcnt lgkmcnt(4)
	v_mfma_f32_32x32x16_f16 v[16:31], v[108:111], v[200:203], v[16:31]
	ds_read_b128 v[108:111], v13 offset:31264
	v_sub_f32_e32 v6, v88, v0
	v_exp_f32_e32 v6, v6
	v_sub_f32_e32 v7, v89, v0
	v_exp_f32_e32 v7, v7
	v_sub_f32_e32 v8, v90, v0
	v_exp_f32_e32 v8, v8
	v_sub_f32_e32 v9, v91, v0
	s_waitcnt lgkmcnt(4)
	v_mfma_f32_32x32x16_f16 v[64:79], v[96:99], v[242:245], v[64:79]
	v_exp_f32_e32 v9, v9
	v_add_f32_e32 v14, v14, v6
	v_add_f32_e32 v14, v14, v7
	v_add_f32_e32 v14, v14, v8
	v_add_f32_e32 v14, v14, v9
	v_cvt_pk_f16_f32 v2, v6, v7
	v_cvt_pk_f16_f32 v3, v8, v9
	s_waitcnt lgkmcnt(3)
	v_mfma_f32_32x32x16_f16 v[48:63], v[100:103], v[242:245], v[48:63]
	v_sub_f32_e32 v6, v92, v0
	v_exp_f32_e32 v6, v6
	v_sub_f32_e32 v7, v93, v0
	v_exp_f32_e32 v7, v7
	v_sub_f32_e32 v8, v94, v0
	v_exp_f32_e32 v8, v8
	v_sub_f32_e32 v9, v95, v0
	s_waitcnt lgkmcnt(2)
	v_mfma_f32_32x32x16_f16 v[32:47], v[104:107], v[242:245], v[32:47]
	v_exp_f32_e32 v9, v9
	v_add_f32_e32 v14, v14, v6
	v_add_f32_e32 v14, v14, v7
	v_add_f32_e32 v14, v14, v8
	v_add_f32_e32 v14, v14, v9
	v_cvt_pk_f16_f32 v4, v6, v7
	v_cvt_pk_f16_f32 v5, v8, v9
	ds_write2_b64 v228, v[2:3], v[4:5] offset0:12 offset1:14
	ds_bpermute_b32 v15, v232, v14
	s_waitcnt lgkmcnt(2)
	v_mfma_f32_32x32x16_f16 v[16:31], v[108:111], v[242:245], v[16:31]
	ds_read_b128 v[246:249], v12 offset:64
	ds_read_b128 v[8:11], v12 offset:96
	ds_read_b128 v[80:83], v13 offset:17472
	ds_read_b128 v[84:87], v13 offset:22080
	ds_read_b128 v[88:91], v13 offset:26688
	ds_read_b128 v[92:95], v13 offset:31296
	ds_read_b128 v[96:99], v13 offset:17504
	ds_read_b128 v[100:103], v13 offset:22112
	ds_read_b128 v[104:107], v13 offset:26720
	ds_read_b128 v[108:111], v13 offset:31328
	s_waitcnt lgkmcnt(10)
	v_add_f32_e32 v14, v14, v15
	v_add_f32_e32 v171, v14, v171
	s_waitcnt lgkmcnt(7)
	v_mfma_f32_32x32x16_f16 v[64:79], v[80:83], v[246:249], v[64:79]
	s_waitcnt lgkmcnt(6)
	v_mfma_f32_32x32x16_f16 v[48:63], v[84:87], v[246:249], v[48:63]
	s_waitcnt lgkmcnt(5)
	v_mfma_f32_32x32x16_f16 v[32:47], v[88:91], v[246:249], v[32:47]
	s_waitcnt lgkmcnt(4)
	v_mfma_f32_32x32x16_f16 v[16:31], v[92:95], v[246:249], v[16:31]
	s_waitcnt lgkmcnt(3)
	v_mfma_f32_32x32x16_f16 v[64:79], v[96:99], v[8:11], v[64:79]
	s_waitcnt lgkmcnt(2)
	v_mfma_f32_32x32x16_f16 v[48:63], v[100:103], v[8:11], v[48:63]
	s_waitcnt lgkmcnt(1)
	v_mfma_f32_32x32x16_f16 v[32:47], v[104:107], v[8:11], v[32:47]
	s_waitcnt lgkmcnt(0)
	v_mfma_f32_32x32x16_f16 v[16:31], v[108:111], v[8:11], v[16:31]
	s_branch .Lattn_tile_end
	.p2align	6

; __device__ __forceinline__ void gla_group_combine(const Frame& F, int l, bool last, int b, int h, int role, int nroles, unsigned* gwd, bool arrive) {
;     ...
;     for (int r4 = (role * 8 + w) * 4; r4 < nrow; r4 += nroles * 32) {
;         const int rl = r4 + (lane >> 4);
;         const int row = (rl < SEQ) ? b * SEQ + rl : TL + b * CTXL + (rl - SEQ);
;         const size_t o = (size_t)row * DM + h * 256 + (lane & 15) * 16;
;         const f16x8 a0 = *(const f16x8*)(F.H16 + o), a1 = *(const f16x8*)(F.H16 + o + 8), b0 = *(const f16x8*)(F.OB + o), b1 = *(const f16x8*)(F.OB + o + 8);
;         f16* gp = F.Z + (size_t)row * ZLD + Z_GR + h * 256 + (lane & 15) * 16;
;         const f16x8 r0 = *(const f16x8*)gp, r1 = *(const f16x8*)(gp + 8);
.LBB0_633:
	v_add_u32_e32 v22, s2, v24
	v_mov_b32_e32 v23, s3
	v_mov_b32_e32 v29, s4
	v_cmp_gt_i32_e32 vcc, s36, v22
	v_mov_b64_e32 v[20:21], s[22:23]
	s_addk_i32 s2, 0x100
	v_cndmask_b32_e32 v23, v23, v29, vcc
	v_add_u32_e32 v22, v22, v23
	v_ashrrev_i32_e32 v23, 31, v22
	v_mad_i64_i32 v[20:21], s[6:7], v22, s14, v[20:21]
	v_lshlrev_b64 v[22:23], 10, v[22:23]
	v_lshl_add_u64 v[20:21], s[8:9], 1, v[20:21]
	v_lshl_add_u64 v[22:23], v[22:23], 0, v[18:19]
	v_lshl_add_u64 v[30:31], v[20:21], 0, v[0:1]
	v_lshlrev_b64 v[38:39], 1, v[22:23]
	v_lshl_add_u64 v[20:21], v[30:31], 0, s[28:29]
	v_add_co_u32_e32 v22, vcc, s36, v30
	v_lshl_add_u64 v[46:47], s[52:53], 0, v[38:39]
	v_lshl_add_u64 v[50:51], s[54:55], 0, v[38:39]
	v_addc_co_u32_e32 v23, vcc, 0, v31, vcc
	global_load_dwordx4 v[30:33], v[20:21], off offset:16
	global_load_dwordx4 v[34:37], v[22:23], off offset:3072
	global_load_dwordx4 v[38:41], v[46:47], off offset:16
	global_load_dwordx4 v[42:45], v[50:51], off offset:16
	s_nop 0
	global_load_dwordx4 v[46:49], v[46:47], off
	s_nop 0
	global_load_dwordx4 v[50:53], v[50:51], off
	s_cmp_lt_i32 s2, s0
	s_waitcnt vmcnt(0)
	.p2align	6

; #define LAS __attribute__((address_space(3)))
; __device__ __forceinline__ unsigned pk_bf16(float lo, float hi) { f32x2 v; v.x = lo; v.y = hi; const bf16x2_t b = __builtin_convertvector(v, bf16x2_t); return __builtin_bit_cast(unsigned, b); }
; __device__ __forceinline__ void phase_gla(const Frame& F, int l, int gi, int ng, bool last, unsigned* cw) {
;     ...
;             { const int cb = chunk_base(s), i0 = it * 32 + 4 * hh; const long rs = dir ? -(long)DM : (long)DM;
;               f16* ob = Oout + (size_t)(cb + (dir ? 63 - i0 : i0)) * DM + h * 256 + sl * 128 + et * 32 + r32;
; #pragma unroll
;               for (int e = 0; e < 16; ++e) ob[((e & 3) + 8 * (e >> 2)) * rs] = (f16)oacc[e]; }
; #pragma unroll
;             for (int q = 0; q < 2; ++q) {
; #pragma unroll
;                 for (int g4 = 0; g4 < 4; ++g4) { const f32x4 ev = *(const LAS f32x4*)(lds + GL_EB + (dt * 32 + g4 * 8 + hh * 4) * 4);
; #pragma unroll
;                     for (int e = 0; e < 4; ++e) Sacc[q][g4 * 4 + e] *= ev[e]; }
; #pragma unroll
;                 for (int ks = 0; ks < 4; ++ks) {
;                     const s16x8 a = *(const LAS s16x8*)(lds + GL_KT + ((dt * 32 + r32) * 72 + ks * 16 + hh * 8) * 2);
;                     const s16x8 bb = *(const LAS s16x8*)(lds + GL_VT + (((e2 + q) * 32 + r32) * 72 + ks * 16 + hh * 8) * 2);
;                     Sacc[q] = __builtin_amdgcn_mfma_f32_32x32x16_bf16(a, bb, Sacc[q], 0, 0, 0); }
; #pragma unroll
;                 for (int g4 = 0; g4 < 4; ++g4)
;                     *(LAS u32x2*)(lds + GL_ST + (((e2 + q) * 32 + r32) * 136 + dt * 32 + g4 * 8 + hh * 4) * 2) = (u32x2){pk_bf16(Sacc[q][g4 * 4], Sacc[q][g4 * 4 + 1]), pk_bf16(Sacc[q][g4 * 4 + 2], Sacc[q][g4 * 4 + 3])};
;             }
;             __syncthreads();
.LBB0_643:
	s_waitcnt lgkmcnt(7)
	v_pk_mul_f32 v[2:3], v[2:3], v[230:231]
	v_pk_mul_f32 v[4:5], v[4:5], v[232:233]
	v_pk_mul_f32 v[18:19], v[18:19], v[230:231]
	v_pk_mul_f32 v[20:21], v[20:21], v[232:233]
	s_waitcnt lgkmcnt(6)
	v_pk_mul_f32 v[6:7], v[6:7], v[242:243]
	v_pk_mul_f32 v[8:9], v[8:9], v[244:245]
	v_pk_mul_f32 v[22:23], v[22:23], v[242:243]
	v_pk_mul_f32 v[24:25], v[24:25], v[244:245]
	s_waitcnt lgkmcnt(5)
	v_pk_mul_f32 v[10:11], v[10:11], v[246:247]
	v_pk_mul_f32 v[12:13], v[12:13], v[248:249]
	v_pk_mul_f32 v[26:27], v[26:27], v[246:247]
	v_pk_mul_f32 v[28:29], v[28:29], v[248:249]
	s_waitcnt lgkmcnt(4)
	v_pk_mul_f32 v[14:15], v[14:15], v[62:63]
	v_pk_mul_f32 v[16:17], v[16:17], v[64:65]
	v_pk_mul_f32 v[30:31], v[30:31], v[62:63]
	v_pk_mul_f32 v[32:33], v[32:33], v[64:65]
	v_add_u32_e32 v184, s0, v107
	v_readlane_b32 s0, v254, 16
	v_ashrrev_i32_e32 v185, 31, v184
	v_lshlrev_b64 v[184:185], 11, v[184:185]
	v_lshl_add_u64 v[184:185], v[112:113], 0, v[184:185]
	v_add_u32_e32 v189, s0, v130
	v_readlane_b32 s0, v254, 17
	ds_read_b128 v[192:195], v189
	ds_read_b128 v[200:203], v173
	ds_read_b128 v[214:217], v189 offset:32
	ds_read_b128 v[218:221], v173 offset:32
	ds_read_b128 v[222:225], v189 offset:64
	ds_read_b128 v[226:229], v173 offset:64
	ds_read_b128 v[230:233], v189 offset:96
	ds_read_b128 v[242:245], v173 offset:96
	v_cvt_f16_f32_e32 v188, v34
	global_store_short v[184:185], v188, off
	v_lshl_add_u64 v[186:187], s[8:9], 1, v[184:185]
	v_cvt_f16_f32_e32 v190, v35
	global_store_short v[186:187], v190, off
	v_lshl_add_u64 v[186:187], v[186:187], 0, s[10:11]
	v_cvt_f16_f32_e32 v188, v36
	global_store_short v[186:187], v188, off
	v_lshl_add_u64 v[186:187], v[186:187], 0, s[10:11]
	v_cvt_f16_f32_e32 v190, v37
	global_store_short v[186:187], v190, off
	v_lshl_add_u64 v[186:187], v[186:187], 0, s[86:87]
	s_waitcnt lgkmcnt(7)
	v_mfma_f32_32x32x16_bf16 v[2:17], v[50:53], v[192:195], v[2:17]
	v_cvt_f16_f32_e32 v188, v38
	global_store_short v[186:187], v188, off
	v_lshl_add_u64 v[186:187], v[186:187], 0, s[10:11]
	v_cvt_f16_f32_e32 v190, v39
	global_store_short v[186:187], v190, off
	s_waitcnt lgkmcnt(6)
	v_mfma_f32_32x32x16_bf16 v[18:33], v[50:53], v[200:203], v[18:33]
	v_lshl_add_u64 v[186:187], v[186:187], 0, s[10:11]
	v_cvt_f16_f32_e32 v188, v40
	global_store_short v[186:187], v188, off
	v_lshl_add_u64 v[186:187], v[186:187], 0, s[10:11]
	v_cvt_f16_f32_e32 v190, v41
	s_waitcnt lgkmcnt(5)
	v_mfma_f32_32x32x16_bf16 v[2:17], v[54:57], v[214:217], v[2:17]
	global_store_short v[186:187], v190, off
	v_lshl_add_u64 v[186:187], v[186:187], 0, s[86:87]
	v_cvt_f16_f32_e32 v188, v42
	global_store_short v[186:187], v188, off
	v_lshl_add_u64 v[186:187], v[186:187], 0, s[10:11]
	s_waitcnt lgkmcnt(4)
	v_mfma_f32_32x32x16_bf16 v[18:33], v[54:57], v[218:221], v[18:33]
	v_cvt_f16_f32_e32 v190, v43
	global_store_short v[186:187], v190, off
	v_lshl_add_u64 v[186:187], v[186:187], 0, s[10:11]
	v_cvt_f16_f32_e32 v188, v44
	global_store_short v[186:187], v188, off
	s_waitcnt lgkmcnt(3)
	v_mfma_f32_32x32x16_bf16 v[2:17], v[58:61], v[222:225], v[2:17]
	v_lshl_add_u64 v[186:187], v[186:187], 0, s[10:11]
	v_cvt_f16_f32_e32 v190, v45
	global_store_short v[186:187], v190, off
	v_lshl_add_u64 v[186:187], v[186:187], 0, s[86:87]
	v_cvt_f16_f32_e32 v188, v46
	s_waitcnt lgkmcnt(2)
	v_mfma_f32_32x32x16_bf16 v[18:33], v[58:61], v[226:229], v[18:33]
	global_store_short v[186:187], v188, off
	v_lshl_add_u64 v[186:187], v[186:187], 0, s[10:11]
	v_cvt_f16_f32_e32 v190, v47
	global_store_short v[186:187], v190, off
	v_lshl_add_u64 v[186:187], v[186:187], 0, s[10:11]
	s_waitcnt lgkmcnt(1)
	v_mfma_f32_32x32x16_bf16 v[2:17], v[180:183], v[230:233], v[2:17]
	v_cvt_f16_f32_e32 v188, v48
	global_store_short v[186:187], v188, off
	v_lshl_add_u64 v[186:187], v[186:187], 0, s[10:11]
	v_cvt_f16_f32_e32 v190, v49
	global_store_short v[186:187], v190, off
	s_waitcnt lgkmcnt(0)
	v_mfma_f32_32x32x16_bf16 v[18:33], v[180:183], v[242:245], v[18:33]
	v_add_u32_e32 v36, s33, v131
	s_nop 10
	v_cvt_pk_bf16_f32 v34, v2, v3
	v_cvt_pk_bf16_f32 v35, v4, v5
	ds_write_b64 v36, v[34:35]
	v_cvt_pk_bf16_f32 v34, v6, v7
	v_cvt_pk_bf16_f32 v35, v8, v9
	v_add_u32_e32 v36, s0, v131
	ds_write_b64 v36, v[34:35]
	v_cvt_pk_bf16_f32 v34, v10, v11
	v_cvt_pk_bf16_f32 v35, v12, v13
	v_add_u32_e32 v36, s95, v131
	ds_write_b64 v36, v[34:35]
	v_cvt_pk_bf16_f32 v34, v14, v15
	v_cvt_pk_bf16_f32 v35, v16, v17
	v_add_u32_e32 v36, s89, v131
	ds_write_b64 v36, v[34:35]
	v_add_u32_e32 v36, s33, v132
	v_cvt_pk_bf16_f32 v34, v18, v19
	v_cvt_pk_bf16_f32 v35, v20, v21
	ds_write_b64 v36, v[34:35]
	v_cvt_pk_bf16_f32 v34, v22, v23
	v_cvt_pk_bf16_f32 v35, v24, v25
	v_add_u32_e32 v36, s0, v132
	ds_write_b64 v36, v[34:35]
	v_cvt_pk_bf16_f32 v34, v26, v27
	v_cvt_pk_bf16_f32 v35, v28, v29
	v_add_u32_e32 v36, s95, v132
	ds_write_b64 v36, v[34:35]
	v_cvt_pk_bf16_f32 v34, v30, v31
	v_cvt_pk_bf16_f32 v35, v32, v33
	v_add_u32_e32 v36, s89, v132
	ds_write_b64 v36, v[34:35]
	s_add_i32 s37, s37, -1
	s_add_i32 s7, s7, 1
	s_cmp_eq_u32 s7, 64
	s_waitcnt lgkmcnt(0)
	s_barrier
	s_cbranch_scc1 .LBB0_666
	.p2align	6

; __device__ __forceinline__ void gla_group_combine(const Frame& F, int l, bool last, int b, int h, int role, int nroles, unsigned* gwd, bool arrive) {
;     ...
;     for (int r4 = (role * 8 + w) * 4; r4 < nrow; r4 += nroles * 32) {
;         const int rl = r4 + (lane >> 4);
;         const int row = (rl < SEQ) ? b * SEQ + rl : TL + b * CTXL + (rl - SEQ);
;         const size_t o = (size_t)row * DM + h * 256 + (lane & 15) * 16;
;         const f16x8 a0 = *(const f16x8*)(F.H16 + o), a1 = *(const f16x8*)(F.H16 + o + 8), b0 = *(const f16x8*)(F.OB + o), b1 = *(const f16x8*)(F.OB + o + 8);
;         f16* gp = F.Z + (size_t)row * ZLD + Z_GR + h * 256 + (lane & 15) * 16;
;         const f16x8 r0 = *(const f16x8*)gp, r1 = *(const f16x8*)(gp + 8);
.LBB0_680:
	v_add_u32_e32 v22, s0, v133
	v_mov_b32_e32 v23, s1
	v_mov_b32_e32 v28, s6
	v_cmp_gt_i32_e32 vcc, s36, v22
	v_mov_b64_e32 v[20:21], s[22:23]
	s_addk_i32 s0, 0x100
	v_cndmask_b32_e32 v23, v23, v28, vcc
	v_add_u32_e32 v22, v22, v23
	v_ashrrev_i32_e32 v23, 31, v22
	v_mad_i64_i32 v[20:21], s[2:3], v22, s14, v[20:21]
	v_lshlrev_b64 v[22:23], 10, v[22:23]
	v_lshl_add_u64 v[20:21], s[30:31], 1, v[20:21]
	v_lshl_add_u64 v[22:23], v[22:23], 0, v[18:19]
	v_lshl_add_u64 v[28:29], v[20:21], 0, v[0:1]
	v_lshlrev_b64 v[36:37], 1, v[22:23]
	v_lshl_add_u64 v[20:21], v[28:29], 0, s[34:35]
	v_add_co_u32_e32 v22, vcc, s36, v28
	v_lshl_add_u64 v[44:45], s[52:53], 0, v[36:37]
	v_lshl_add_u64 v[48:49], s[54:55], 0, v[36:37]
	v_addc_co_u32_e32 v23, vcc, 0, v29, vcc
	global_load_dwordx4 v[28:31], v[20:21], off offset:16
	global_load_dwordx4 v[32:35], v[22:23], off offset:3072
	global_load_dwordx4 v[36:39], v[44:45], off offset:16
	global_load_dwordx4 v[40:43], v[48:49], off offset:16
	s_nop 0
	global_load_dwordx4 v[44:47], v[44:45], off
	s_nop 0
	global_load_dwordx4 v[48:51], v[48:49], off
	s_cmp_lt_i32 s0, s38
	s_waitcnt vmcnt(0)
	.p2align	6

; __device__ __forceinline__ float wave_sum(float v) {
; #pragma unroll
;     for (int o = 32; o >= 1; o >>= 1) v += __shfl_xor(v, o);
;     return v;
; __device__ __forceinline__ void phase_norm(const Frame& F, const float* xl, const float* xc, const f16* x16, int l, int which, int r0, int nrows, int ci, int nc) {
;     const float* nw = F.in[6] + ((size_t)l * 3 + which) * DM;
;     const int gw = r0 + ci * 8 + F.wave, nw_ = nc * 8;
;     for (int row = gw; row < nrows; row += nw_) {
;         const bool lat = row < TL; const int mi = lat ? (row >> 12) : 8;
;         const float* sh = F.MOD + ((size_t)l * 9 + mi) * NMOD + (3 * which) * DM; const float* sc = sh + DM;
;         float v[2][8]; float ss = 0.f;
;         if (x16) {
;             const f16* xp = x16 + (size_t)row * DM;
; #pragma unroll
;             for (int j = 0; j < 2; ++j) { const f16x8 t = *(const f16x8*)(xp + j * 512 + F.lane * 8);
.LBB0_958:
	s_or_b64 exec, exec, s[4:5]
	v_readlane_b32 s4, v253, 0
	v_readlane_b32 s6, v253, 2
	s_mov_b64 s[2:3], s[84:85]
	v_mov_b32_e32 v6, v234
	s_mov_b32 s8, s6
	s_mov_b32 s0, s80
	s_waitcnt lgkmcnt(0)
	s_barrier
	v_readlane_b32 s7, v253, 3
	s_lshl_b32 s7, s0, 3
	v_readfirstlane_b32 s4, v6
	s_ashr_i32 s6, s4, 6
	s_add_i32 s0, s7, s6
	s_cmp_ge_i32 s0, s1
	v_readlane_b32 s5, v253, 1
	s_cbranch_scc1 .LBB0_961
	v_and_b32_e32 v0, 64, v237
	v_add_u32_e32 v0, 64, v0
	v_xor_b32_e32 v2, 32, v237
	v_cmp_lt_i32_e32 vcc, v2, v0
	s_load_dwordx2 s[10:11], s[2:3], 0x30
	s_load_dwordx2 s[4:5], s[2:3], 0xc0
	v_cndmask_b32_e32 v2, v237, v2, vcc
	v_lshlrev_b32_e32 v10, 2, v2
	v_xor_b32_e32 v2, 16, v237
	v_cmp_lt_i32_e32 vcc, v2, v0
	v_readlane_b32 s3, v254, 27
	v_lshlrev_b32_e64 v8, 3, s8
	v_cndmask_b32_e32 v2, v237, v2, vcc
	v_lshlrev_b32_e32 v11, 2, v2
	v_xor_b32_e32 v2, 8, v237
	v_cmp_lt_i32_e32 vcc, v2, v0
	s_waitcnt lgkmcnt(0)
	s_add_u32 s3, s10, s3
	v_readlane_b32 s8, v254, 26
	v_cndmask_b32_e32 v2, v237, v2, vcc
	v_lshlrev_b32_e32 v12, 2, v2
	v_xor_b32_e32 v2, 4, v237
	v_cmp_lt_i32_e32 vcc, v2, v0
	s_addc_u32 s9, s11, s8
	s_add_u32 s8, s3, 0x2000
	v_cndmask_b32_e32 v2, v237, v2, vcc
	v_lshlrev_b32_e32 v13, 2, v2
	v_xor_b32_e32 v2, 2, v237
	v_cmp_lt_i32_e32 vcc, v2, v0
	s_addc_u32 s9, s9, 0
	s_ashr_i32 s3, s6, 31
	v_cndmask_b32_e32 v2, v237, v2, vcc
	s_waitcnt vmcnt(0)
	v_lshlrev_b32_e32 v14, 2, v2
	v_xor_b32_e32 v2, 1, v237
	v_cmp_lt_i32_e32 vcc, v2, v0
	v_ashrrev_i32_e32 v9, 31, v8
	v_readfirstlane_b32 s2, v8
	v_cndmask_b32_e32 v0, v237, v2, vcc
	v_lshlrev_b32_e32 v15, 2, v0
	v_lshlrev_b32_e32 v0, 3, v6
	v_and_b32_e32 v16, 0x1f8, v0
	v_lshlrev_b32_e32 v0, 2, v16
	v_or_b32_e32 v18, 0x200, v16
	v_lshl_add_u64 v[2:3], s[8:9], 0, v[0:1]
	v_lshlrev_b32_e32 v0, 2, v18
	v_lshl_add_u64 v[4:5], s[8:9], 0, v[0:1]
	s_ashr_i32 s8, s7, 31
	s_add_u32 s6, s6, s7
	s_addc_u32 s7, s3, s8
	s_lshl_b64 s[6:7], s[6:7], 11
	v_and_b32_e32 v0, 63, v6
	s_add_u32 s6, s4, s6
	v_lshlrev_b32_e32 v0, 4, v0
	s_addc_u32 s7, s5, s7
	v_lshl_add_u64 v[6:7], s[6:7], 0, v[0:1]
	s_mov_b64 s[6:7], 0x6948000
	v_lshl_add_u64 v[6:7], v[6:7], 0, s[6:7]
	v_lshlrev_b64 v[8:9], 11, v[8:9]
	v_lshlrev_b32_e32 v0, 2, v16
	v_lshlrev_b32_e32 v16, 2, v18
	.p2align	6

; __device__ __forceinline__ void phase_norm(const Frame& F, const float* xl, const float* xc, const f16* x16, int l, int which, int r0, int nrows, int ci, int nc) {
;     const float* nw = F.in[6] + ((size_t)l * 3 + which) * DM;
;     const int gw = r0 + ci * 8 + F.wave, nw_ = nc * 8;
;     for (int row = gw; row < nrows; row += nw_) {
;         const bool lat = row < TL; const int mi = lat ? (row >> 12) : 8;
;         const float* sh = F.MOD + ((size_t)l * 9 + mi) * NMOD + (3 * which) * DM; const float* sc = sh + DM;
;         float v[2][8]; float ss = 0.f;
;         if (x16) {
;             const f16* xp = x16 + (size_t)row * DM;
; #pragma unroll
;             for (int j = 0; j < 2; ++j) { const f16x8 t = *(const f16x8*)(xp + j * 512 + F.lane * 8);
; __global__ void __launch_bounds__(NTHR, 2) mega(Params p) {
;     ...
;             if (!last) { int extra = (TL / 256) * 4 + ((mrows - TL) / 128) * 4 - 2 * F.G; if (extra < 0 || extra >= F.G) extra = 0;
;                 if (F.bid >= extra) { sub_wait(aw, (unsigned)F.G); phase_norm(F, F.in[0], F.in[2], F.XH, l + 1, 0, 0, TL, F.bid - extra, F.G - extra); } } }
.LBB0_1198:
	s_or_b64 exec, exec, s[4:5]
	s_sub_i32 s1, s1, s12
	s_ashr_i32 s2, s17, 6
	s_lshl_b32 s1, s1, 3
	s_add_i32 s4, s1, s2
	s_cmpk_gt_i32 s4, 0x7fff
	s_waitcnt lgkmcnt(0)
	s_barrier
	s_cbranch_scc1 .LBB0_1201
	v_and_b32_e32 v0, 64, v237
	v_add_u32_e32 v0, 64, v0
	v_xor_b32_e32 v2, 32, v237
	v_cmp_lt_i32_e32 vcc, v2, v0
	s_sub_i32 s0, s0, s12
	s_add_i32 s1, s90, 1
	v_cndmask_b32_e32 v2, v237, v2, vcc
	v_lshlrev_b32_e32 v6, 2, v2
	v_xor_b32_e32 v2, 16, v237
	v_cmp_lt_i32_e32 vcc, v2, v0
	s_lshl_b32 s10, s0, 3
	s_mul_i32 s2, s1, 0x3000
	v_cndmask_b32_e32 v2, v237, v2, vcc
	v_lshlrev_b32_e32 v7, 2, v2
	v_xor_b32_e32 v2, 8, v237
	v_cmp_lt_i32_e32 vcc, v2, v0
	s_mul_hi_u32 s0, s1, 0x3000
	s_add_u32 s2, s8, s2
	v_cndmask_b32_e32 v2, v237, v2, vcc
	v_lshlrev_b32_e32 v8, 2, v2
	v_xor_b32_e32 v2, 4, v237
	v_cmp_lt_i32_e32 vcc, v2, v0
	s_addc_u32 s3, s9, s0
	s_ashr_i32 s5, s4, 31
	v_cndmask_b32_e32 v2, v237, v2, vcc
	v_lshlrev_b32_e32 v9, 2, v2
	v_xor_b32_e32 v2, 2, v237
	v_cmp_lt_i32_e32 vcc, v2, v0
	s_mul_hi_u32 s0, s1, 9
	s_mul_i32 s1, s1, 9
	v_cndmask_b32_e32 v2, v237, v2, vcc
	v_lshlrev_b32_e32 v10, 2, v2
	v_xor_b32_e32 v2, 1, v237
	v_cmp_lt_i32_e32 vcc, v2, v0
	s_nop 1
	v_cndmask_b32_e32 v0, v237, v2, vcc
	v_lshlrev_b32_e32 v11, 2, v0
	v_lshlrev_b32_e32 v0, 3, v221
	v_and_b32_e32 v12, 0x1f8, v0
	v_lshlrev_b32_e32 v0, 2, v12
	v_lshl_add_u64 v[2:3], s[2:3], 0, v[0:1]
	s_lshl_b64 s[2:3], s[4:5], 11
	v_and_b32_e32 v0, 63, v221
	s_add_u32 s2, s6, s2
	v_lshlrev_b32_e32 v0, 4, v0
	s_addc_u32 s3, s7, s3
	v_or_b32_e32 v14, 0x200, v12
	v_lshl_add_u64 v[4:5], s[2:3], 0, v[0:1]
	s_mov_b64 s[2:3], 0x6948000
	s_ashr_i32 s11, s10, 31
	v_lshl_add_u64 v[4:5], v[4:5], 0, s[2:3]
	s_lshl_b64 s[8:9], s[10:11], 11
	v_lshlrev_b32_e32 v0, 2, v12
	v_lshlrev_b32_e32 v12, 2, v14
	.p2align	6
